# exp_pooldbl
# baseline (speedup 1.0000x reference)
; __device__ __forceinline__ void phase_mixers(const Params& p, int cidx, int layer) {
;   __shared__ int s_item;
;   int* ctr = (int*)(p.ws + WS_CTR) + cidx;
;   constexpr int N_SSM = 128 * (1 + (MIXDBL & 1)), N_POOL = 256 * (1 + ((MIXDBL >> 2) & 1)), N_ATT = 512 * (1 + ((MIXDBL >> 1) & 1));
;   const int n_cv = (layer == 0) ? CV_B * (1 + ((MIXDBL >> 3) & 1)) : 0;
.LBB0_68:
	s_and_b64 vcc, exec, s[8:9]
	s_cbranch_vccz .LBB0_216
	s_cmp_gt_i32 s57, 0
	s_mov_b64 s[8:9], -1
	s_cbranch_scc0 .LBB0_218
	s_lshl_b32 s6, s64, 1
	s_ashr_i32 s7, s6, 31
	s_lshl_b64 s[6:7], s[6:7], 2
	s_add_u32 s6, s86, s6
	s_addc_u32 s7, s87, s7
	s_add_u32 s28, s6, 0x43d10000
	s_addc_u32 s29, s7, 0
	s_add_i32 s6, s44, 4
	s_cmp_lt_u32 s6, 11
	s_movk_i32 s6, 0x724
	v_writelane_b32 v255, s57, 3
	s_cselect_b32 s11, s6, 0x480
	s_mov_b32 s10, s64
	s_ashr_i32 s65, s64, 31
	s_lshl_b32 s8, s64, 10
	v_writelane_b32 v255, s10, 4
	s_lshl_b64 s[6:7], s[64:65], 19
	s_ashr_i32 s9, s8, 31
	v_writelane_b32 v255, s11, 5
	s_lshl_b32 s10, s64, 6
	s_add_u32 s12, s86, 0x10880000
	v_writelane_b32 v255, s12, 6
	s_addc_u32 s12, s87, 0
	v_writelane_b32 v255, s12, 7
	v_readlane_b32 s12, v254, 33
	v_readlane_b32 s18, v254, 39
	v_readlane_b32 s19, v254, 40
	s_add_u32 s12, s18, 0x100000
	v_writelane_b32 v255, s12, 8
	s_addc_u32 s12, s19, 0
	v_readlane_b32 s13, v254, 34
	v_writelane_b32 v255, s12, 9
	s_add_u32 s12, s86, 0x10400000
	v_readlane_b32 s64, v254, 49
	s_addc_u32 s13, s87, 0
	v_readlane_b32 s69, v254, 54
	v_readlane_b32 s74, v254, 59
	v_writelane_b32 v255, s12, 10
	v_readlane_b32 s68, v254, 53
	v_readlane_b32 s75, v254, 60
	s_add_u32 s69, s74, 0x800000
	v_writelane_b32 v255, s13, 11
	s_mov_b32 s68, s10
	s_addc_u32 s10, s75, 0
	v_readlane_b32 s65, v254, 50
	v_readlane_b32 s79, v255, 0
	v_writelane_b32 v255, s10, 12
	s_add_u32 s10, s86, 0xe000000
	s_mov_b32 s65, s11
	s_addc_u32 s11, s87, 0
	v_writelane_b32 v255, s10, 13
	v_readlane_b32 s16, v254, 37
	v_readlane_b32 s17, v254, 38
	v_writelane_b32 v255, s11, 14
	s_add_u32 s10, s80, 0x4000000
	v_writelane_b32 v255, s10, 15
	s_addc_u32 s10, s81, 0
	v_writelane_b32 v255, s10, 16
	s_add_u32 s10, s86, 0x6000000
	s_addc_u32 s11, s87, 0
	v_writelane_b32 v255, s10, 17
	v_readlane_b32 s70, v254, 55
	v_readlane_b32 s71, v254, 56
	v_writelane_b32 v255, s11, 18
	s_add_u32 s10, s16, 0xc000000
	v_writelane_b32 v255, s10, 19
	s_addc_u32 s10, s17, 0
	v_writelane_b32 v255, s10, 20
	s_add_u32 s10, s86, 0x10000000
	s_addc_u32 s11, s87, 0
	v_writelane_b32 v255, s10, 21
	v_readlane_b32 s20, v254, 41
	v_readlane_b32 s78, v254, 63
	v_writelane_b32 v255, s11, 22
	s_add_u32 s10, s86, 0xc000000
	s_addc_u32 s11, s87, 0
	s_add_u32 s70, s86, 0x43d14100
	s_addc_u32 s71, s87, 0
	s_add_u32 s74, s86, 0x14900000
	s_addc_u32 s75, s87, 0
	s_lshl_b64 s[8:9], s[8:9], 2
	v_readlane_b32 s21, v254, 42
	s_add_u32 s78, s20, s8
	s_addc_u32 s79, s21, s9
	v_writelane_b32 v255, s10, 23
	s_add_u32 s12, s86, 0x22900000
	s_addc_u32 s13, s87, 0
	v_writelane_b32 v255, s11, 24
	v_writelane_b32 v255, s12, 25
	v_readlane_b32 s72, v254, 57
	v_readlane_b32 s73, v254, 58
	v_writelane_b32 v255, s13, 26
	s_add_u32 s12, s86, 0x3f900000
	v_writelane_b32 v255, s12, 27
	s_addc_u32 s12, s87, 0
	v_writelane_b32 v255, s12, 28
	s_add_u32 s12, s86, 0x41d00000
	v_writelane_b32 v255, s12, 29
	s_addc_u32 s12, s87, 0
	v_writelane_b32 v255, s12, 30
	s_add_u32 s12, s86, 0x2e900000
	v_writelane_b32 v255, s12, 31
	s_addc_u32 s12, s87, 0
	v_writelane_b32 v255, s12, 32
	s_add_u32 s12, s86, 0x43d00000
	v_writelane_b32 v255, s12, 33
	s_addc_u32 s12, s87, 0
	v_writelane_b32 v255, s12, 34
	s_add_u32 s8, s72, s8
	v_writelane_b32 v255, s8, 35
	s_addc_u32 s8, s73, s9
	s_add_u32 s6, s86, s6
	s_addc_u32 s7, s87, s7
	v_writelane_b32 v255, s8, 36
	s_add_u32 s8, s6, 0x10860000
	s_addc_u32 s9, s7, 0
	v_writelane_b32 v255, s8, 37
	v_readlane_b32 s76, v254, 61
	v_readlane_b32 s66, v254, 51
	v_writelane_b32 v255, s9, 38
	v_writelane_b32 v255, s44, 39
	v_readlane_b32 s67, v254, 52
	v_readlane_b32 s77, v254, 62
	v_writelane_b32 v255, s45, 40
	s_add_u32 s76, s86, 0x3fd03c00
	v_writelane_b32 v255, s46, 41
	s_mov_b64 s[66:67], s[28:29]
	s_mov_b64 s[72:73], s[6:7]
	s_addc_u32 s77, s87, 0
	v_writelane_b32 v255, s47, 42
	v_readlane_b32 s14, v254, 35
	v_readlane_b32 s15, v254, 36
	v_readlane_b32 s22, v254, 43
	v_readlane_b32 s23, v254, 44
	v_readlane_b32 s24, v254, 45
	v_readlane_b32 s25, v254, 46
	v_readlane_b32 s26, v254, 47
	v_readlane_b32 s27, v254, 48
	s_branch .LBB0_73

; __device__ __forceinline__ void phase_mixers(const Params& p, int cidx, int layer) {
;     ...
;     const int it = s_item;
;     if (it >= N_SSM + N_POOL + N_ATT + n_cv) break;
;     if (it < N_SSM) ssm_item(p, layer, it & 127, tidx);
;     else if (it < N_SSM + N_POOL) pool_block_item(p, layer, (it - N_SSM) & 255, tidx);
;     else if (it < N_SSM + N_POOL + N_ATT) attn_wave_item(p, ((it - N_SSM - N_POOL) & 511) * 8 + wid, tidx);
;     else cv_item_B(p, (it - N_SSM - N_POOL - N_ATT) % CV_B, tidx);
.LBB0_77:
	s_or_b64 exec, exec, s[6:7]
	s_waitcnt lgkmcnt(0)
	s_barrier
	ds_read_b32 v0, v163 offset:20
	s_mov_b64 s[6:7], -1
	s_waitcnt lgkmcnt(0)
	v_cmp_le_i32_e32 vcc, s65, v0
	v_readfirstlane_b32 s64, v0
	s_cbranch_vccnz .LBB0_72
	v_ashrrev_i32_e32 v97, 6, v164
	s_cmp_lt_u32 s64, 0x180
	s_cbranch_scc1 .Lid_done
	s_sub_u32 s64, s64, 0x100
